# GEMM K-loops: counter/pointer/exit-test SALU block rotated in front of the loop-back barrier (loop-edge edit)
# speedup vs baseline: 1.0072x; 1.0072x over previous
.LBB0_102:
	ds_read_b128 v[128:131], v151
	ds_read_b128 v[132:135], v151 offset:1024
	ds_read_b128 v[136:139], v151 offset:2048
	ds_read_b128 v[140:143], v151 offset:3072
	ds_read_b128 v[170:173], v182
	ds_read_b128 v[174:177], v182 offset:1024
	ds_read_b128 v[206:209], v182 offset:2048
	ds_read_b128 v[210:213], v182 offset:3072
	s_add_u32 s10, s8, 0xfffc0080
	s_addc_u32 s11, s9, -1
	s_cmp_eq_u32 s33, 12
	s_cselect_b32 s13, s0, s11
	s_cselect_b32 s12, s1, s10
	s_cselect_b32 s11, s2, s20
	s_cselect_b32 s10, s3, s7
	v_lshl_add_u64 v[178:179], s[8:9], 0, v[166:167]
	s_add_i32 m0, s19, 0xc000
	ds_read_b128 v[214:217], v183
	ds_read_b128 v[218:221], v183 offset:1024
	ds_read_b128 v[222:225], v183 offset:2048
	ds_read_b128 v[226:229], v183 offset:3072
	ds_read_b128 v[230:233], v183 offset:4096
	ds_read_b128 v[234:237], v183 offset:5120
	ds_read_b128 v[238:241], v183 offset:6144
	ds_read_b128 v[242:245], v183 offset:7168
	global_load_lds_dwordx4 v[178:179], off
	v_lshl_add_u64 v[178:179], s[8:9], 0, v[168:169]
	s_add_i32 m0, s19, 0xe000
	s_nop 0
	global_load_lds_dwordx4 v[178:179], off
	s_waitcnt vmcnt(8)
	s_waitcnt lgkmcnt(0)
	s_barrier
	s_setprio 1
	s_waitcnt lgkmcnt(0)
	v_mfma_f32_16x16x32_bf16 v[124:127], v[128:131], v[214:217], v[124:127]
	v_mfma_f32_16x16x32_bf16 v[120:123], v[136:139], v[214:217], v[120:123]
	v_mfma_f32_16x16x32_bf16 v[108:111], v[128:131], v[222:225], v[108:111]
	v_mfma_f32_16x16x32_bf16 v[104:107], v[136:139], v[222:225], v[104:107]
	v_mfma_f32_16x16x32_bf16 v[92:95], v[128:131], v[230:233], v[92:95]
	v_mfma_f32_16x16x32_bf16 v[88:91], v[136:139], v[230:233], v[88:91]
	v_mfma_f32_16x16x32_bf16 v[76:79], v[128:131], v[238:241], v[76:79]
	v_mfma_f32_16x16x32_bf16 v[72:75], v[136:139], v[238:241], v[72:75]
	v_mfma_f32_16x16x32_bf16 v[124:127], v[132:135], v[218:221], v[124:127]
	v_mfma_f32_16x16x32_bf16 v[120:123], v[140:143], v[218:221], v[120:123]
	v_mfma_f32_16x16x32_bf16 v[108:111], v[132:135], v[226:229], v[108:111]
	v_mfma_f32_16x16x32_bf16 v[104:107], v[140:143], v[226:229], v[104:107]
	v_mfma_f32_16x16x32_bf16 v[92:95], v[132:135], v[234:237], v[92:95]
	v_mfma_f32_16x16x32_bf16 v[88:91], v[140:143], v[234:237], v[88:91]
	v_mfma_f32_16x16x32_bf16 v[76:79], v[132:135], v[242:245], v[76:79]
	v_mfma_f32_16x16x32_bf16 v[72:75], v[140:143], v[242:245], v[72:75]
	s_setprio 0
	s_setprio 1
	v_mfma_f32_16x16x32_bf16 v[116:119], v[170:173], v[214:217], v[116:119]
	v_mfma_f32_16x16x32_bf16 v[112:115], v[206:209], v[214:217], v[112:115]
	v_mfma_f32_16x16x32_bf16 v[100:103], v[170:173], v[222:225], v[100:103]
	v_mfma_f32_16x16x32_bf16 v[96:99], v[206:209], v[222:225], v[96:99]
	v_mfma_f32_16x16x32_bf16 v[84:87], v[170:173], v[230:233], v[84:87]
	v_mfma_f32_16x16x32_bf16 v[80:83], v[206:209], v[230:233], v[80:83]
	v_mfma_f32_16x16x32_bf16 v[68:71], v[170:173], v[238:241], v[68:71]
	v_mfma_f32_16x16x32_bf16 v[64:67], v[206:209], v[238:241], v[64:67]
	v_mfma_f32_16x16x32_bf16 v[116:119], v[174:177], v[218:221], v[116:119]
	v_mfma_f32_16x16x32_bf16 v[112:115], v[210:213], v[218:221], v[112:115]
	v_mfma_f32_16x16x32_bf16 v[100:103], v[174:177], v[226:229], v[100:103]
	v_mfma_f32_16x16x32_bf16 v[96:99], v[210:213], v[226:229], v[96:99]
	v_mfma_f32_16x16x32_bf16 v[84:87], v[174:177], v[234:237], v[84:87]
	v_mfma_f32_16x16x32_bf16 v[80:83], v[210:213], v[234:237], v[80:83]
	v_mfma_f32_16x16x32_bf16 v[68:71], v[174:177], v[242:245], v[68:71]
	v_mfma_f32_16x16x32_bf16 v[64:67], v[210:213], v[242:245], v[64:67]
	s_setprio 0
	s_barrier
	s_add_i32 s37, s57, s46
	v_lshl_add_u64 v[178:179], s[10:11], 0, v[154:155]
	s_mov_b32 m0, s37
	ds_read_b128 v[214:217], v183 offset:16384
	ds_read_b128 v[218:221], v183 offset:17408
	ds_read_b128 v[222:225], v183 offset:18432
	ds_read_b128 v[226:229], v183 offset:19456
	ds_read_b128 v[230:233], v183 offset:20480
	ds_read_b128 v[234:237], v183 offset:21504
	ds_read_b128 v[238:241], v183 offset:22528
	ds_read_b128 v[242:245], v183 offset:23552
	global_load_lds_dwordx4 v[178:179], off
	s_add_i32 m0, s37, 0x2000
	s_add_u32 s66, s10, 0x40000
	v_lshl_add_u64 v[246:247], s[10:11], 0, v[158:159]
	s_addc_u32 s67, s11, 0
	s_add_i32 s37, s58, s46
	global_load_lds_dwordx4 v[246:247], off
	v_lshl_add_u64 v[248:249], s[66:67], 0, v[154:155]
	s_mov_b32 m0, s37
	v_lshl_add_u64 v[250:251], s[12:13], 0, v[156:157]
	global_load_lds_dwordx4 v[248:249], off
	v_lshl_add_u64 v[248:249], s[66:67], 0, v[158:159]
	s_add_i32 m0, s37, 0x2000
	s_nop 0
	global_load_lds_dwordx4 v[248:249], off
	v_lshl_add_u64 v[248:249], s[12:13], 0, v[152:153]
	s_mov_b32 m0, s19
	s_nop 0
	global_load_lds_dwordx4 v[248:249], off
	s_mov_b32 m0, s47
	s_nop 0
	global_load_lds_dwordx4 v[250:251], off
	s_waitcnt vmcnt(8)
	s_waitcnt lgkmcnt(0)
	s_barrier
	s_setprio 1
	s_waitcnt lgkmcnt(0)
	v_mfma_f32_16x16x32_bf16 v[60:63], v[128:131], v[214:217], v[60:63]
	v_mfma_f32_16x16x32_bf16 v[56:59], v[136:139], v[214:217], v[56:59]
	v_mfma_f32_16x16x32_bf16 v[44:47], v[128:131], v[222:225], v[44:47]
	v_mfma_f32_16x16x32_bf16 v[40:43], v[136:139], v[222:225], v[40:43]
	v_mfma_f32_16x16x32_bf16 v[28:31], v[128:131], v[230:233], v[28:31]
	v_mfma_f32_16x16x32_bf16 v[24:27], v[136:139], v[230:233], v[24:27]
	v_mfma_f32_16x16x32_bf16 v[12:15], v[128:131], v[238:241], v[12:15]
	v_mfma_f32_16x16x32_bf16 v[8:11], v[136:139], v[238:241], v[8:11]
	v_mfma_f32_16x16x32_bf16 v[60:63], v[132:135], v[218:221], v[60:63]
	v_mfma_f32_16x16x32_bf16 v[56:59], v[140:143], v[218:221], v[56:59]
	v_mfma_f32_16x16x32_bf16 v[44:47], v[132:135], v[226:229], v[44:47]
	v_mfma_f32_16x16x32_bf16 v[40:43], v[140:143], v[226:229], v[40:43]
	v_mfma_f32_16x16x32_bf16 v[28:31], v[132:135], v[234:237], v[28:31]
	v_mfma_f32_16x16x32_bf16 v[24:27], v[140:143], v[234:237], v[24:27]
	v_mfma_f32_16x16x32_bf16 v[12:15], v[132:135], v[242:245], v[12:15]
	v_mfma_f32_16x16x32_bf16 v[8:11], v[140:143], v[242:245], v[8:11]
	s_setprio 0
	s_setprio 1
	v_mfma_f32_16x16x32_bf16 v[52:55], v[170:173], v[214:217], v[52:55]
	v_mfma_f32_16x16x32_bf16 v[48:51], v[206:209], v[214:217], v[48:51]
	v_mfma_f32_16x16x32_bf16 v[36:39], v[170:173], v[222:225], v[36:39]
	v_mfma_f32_16x16x32_bf16 v[32:35], v[206:209], v[222:225], v[32:35]
	v_mfma_f32_16x16x32_bf16 v[20:23], v[170:173], v[230:233], v[20:23]
	v_mfma_f32_16x16x32_bf16 v[16:19], v[206:209], v[230:233], v[16:19]
	v_mfma_f32_16x16x32_bf16 v[4:7], v[170:173], v[238:241], v[4:7]
	v_mfma_f32_16x16x32_bf16 v[0:3], v[206:209], v[238:241], v[0:3]
	v_mfma_f32_16x16x32_bf16 v[52:55], v[174:177], v[218:221], v[52:55]
	v_mfma_f32_16x16x32_bf16 v[48:51], v[210:213], v[218:221], v[48:51]
	v_mfma_f32_16x16x32_bf16 v[36:39], v[174:177], v[226:229], v[36:39]
	v_mfma_f32_16x16x32_bf16 v[32:35], v[210:213], v[226:229], v[32:35]
	v_mfma_f32_16x16x32_bf16 v[20:23], v[174:177], v[234:237], v[20:23]
	v_mfma_f32_16x16x32_bf16 v[16:19], v[210:213], v[234:237], v[16:19]
	v_mfma_f32_16x16x32_bf16 v[4:7], v[174:177], v[242:245], v[4:7]
	v_mfma_f32_16x16x32_bf16 v[0:3], v[210:213], v[242:245], v[0:3]
	s_setprio 0
	s_barrier
	s_add_i32 s37, 0, 0x18000
	s_add_i32 s39, 0, 0x1c000
	v_add_u32_e32 v140, s37, v149
	v_add_u32_e32 v160, s39, v149
	ds_read_b128 v[128:131], v140
	ds_read_b128 v[132:135], v140 offset:1024
	ds_read_b128 v[136:139], v140 offset:2048
	ds_read_b128 v[140:143], v140 offset:3072
	ds_read_b128 v[170:173], v160
	ds_read_b128 v[174:177], v160 offset:1024
	ds_read_b128 v[206:209], v160 offset:2048
	ds_read_b128 v[210:213], v160 offset:3072
	s_add_u32 s12, s12, 0x40000
	s_addc_u32 s13, s13, 0
	s_mov_b32 m0, s48
	v_lshl_add_u64 v[252:253], s[12:13], 0, v[152:153]
	ds_read_b128 v[214:217], v183 offset:32768
	ds_read_b128 v[218:221], v183 offset:33792
	ds_read_b128 v[222:225], v183 offset:34816
	ds_read_b128 v[226:229], v183 offset:35840
	ds_read_b128 v[230:233], v183 offset:36864
	ds_read_b128 v[234:237], v183 offset:37888
	ds_read_b128 v[238:241], v183 offset:38912
	ds_read_b128 v[242:245], v183 offset:39936
	global_load_lds_dwordx4 v[252:253], off
	v_lshl_add_u64 v[252:253], s[12:13], 0, v[156:157]
	s_mov_b32 m0, s49
	s_nop 0
	global_load_lds_dwordx4 v[252:253], off
	s_waitcnt vmcnt(8)
	s_waitcnt lgkmcnt(0)
	s_barrier
	s_setprio 1
	s_waitcnt lgkmcnt(0)
	v_mfma_f32_16x16x32_bf16 v[124:127], v[128:131], v[214:217], v[124:127]
	v_mfma_f32_16x16x32_bf16 v[120:123], v[136:139], v[214:217], v[120:123]
	v_mfma_f32_16x16x32_bf16 v[108:111], v[128:131], v[222:225], v[108:111]
	v_mfma_f32_16x16x32_bf16 v[104:107], v[136:139], v[222:225], v[104:107]
	v_mfma_f32_16x16x32_bf16 v[92:95], v[128:131], v[230:233], v[92:95]
	v_mfma_f32_16x16x32_bf16 v[88:91], v[136:139], v[230:233], v[88:91]
	v_mfma_f32_16x16x32_bf16 v[76:79], v[128:131], v[238:241], v[76:79]
	v_mfma_f32_16x16x32_bf16 v[72:75], v[136:139], v[238:241], v[72:75]
	v_mfma_f32_16x16x32_bf16 v[124:127], v[132:135], v[218:221], v[124:127]
	v_mfma_f32_16x16x32_bf16 v[120:123], v[140:143], v[218:221], v[120:123]
	v_mfma_f32_16x16x32_bf16 v[108:111], v[132:135], v[226:229], v[108:111]
	v_mfma_f32_16x16x32_bf16 v[104:107], v[140:143], v[226:229], v[104:107]
	v_mfma_f32_16x16x32_bf16 v[92:95], v[132:135], v[234:237], v[92:95]
	v_mfma_f32_16x16x32_bf16 v[88:91], v[140:143], v[234:237], v[88:91]
	v_mfma_f32_16x16x32_bf16 v[76:79], v[132:135], v[242:245], v[76:79]
	v_mfma_f32_16x16x32_bf16 v[72:75], v[140:143], v[242:245], v[72:75]
	s_setprio 0
	s_setprio 1
	v_mfma_f32_16x16x32_bf16 v[116:119], v[170:173], v[214:217], v[116:119]
	v_mfma_f32_16x16x32_bf16 v[112:115], v[206:209], v[214:217], v[112:115]
	v_mfma_f32_16x16x32_bf16 v[100:103], v[170:173], v[222:225], v[100:103]
	v_mfma_f32_16x16x32_bf16 v[96:99], v[206:209], v[222:225], v[96:99]
	v_mfma_f32_16x16x32_bf16 v[84:87], v[170:173], v[230:233], v[84:87]
	v_mfma_f32_16x16x32_bf16 v[80:83], v[206:209], v[230:233], v[80:83]
	v_mfma_f32_16x16x32_bf16 v[68:71], v[170:173], v[238:241], v[68:71]
	v_mfma_f32_16x16x32_bf16 v[64:67], v[206:209], v[238:241], v[64:67]
	v_mfma_f32_16x16x32_bf16 v[116:119], v[174:177], v[218:221], v[116:119]
	v_mfma_f32_16x16x32_bf16 v[112:115], v[210:213], v[218:221], v[112:115]
	v_mfma_f32_16x16x32_bf16 v[100:103], v[174:177], v[226:229], v[100:103]
	v_mfma_f32_16x16x32_bf16 v[96:99], v[210:213], v[226:229], v[96:99]
	v_mfma_f32_16x16x32_bf16 v[84:87], v[174:177], v[234:237], v[84:87]
	v_mfma_f32_16x16x32_bf16 v[80:83], v[210:213], v[234:237], v[80:83]
	v_mfma_f32_16x16x32_bf16 v[68:71], v[174:177], v[242:245], v[68:71]
	v_mfma_f32_16x16x32_bf16 v[64:67], v[210:213], v[242:245], v[64:67]
	s_setprio 0
	s_barrier
	s_add_i32 s12, s37, s46
	v_lshl_add_u64 v[178:179], v[178:179], 0, s[24:25]
	s_mov_b32 m0, s12
	ds_read_b128 v[214:217], v183 offset:49152
	ds_read_b128 v[218:221], v183 offset:50176
	ds_read_b128 v[222:225], v183 offset:51200
	ds_read_b128 v[226:229], v183 offset:52224
	ds_read_b128 v[230:233], v183 offset:53248
	ds_read_b128 v[234:237], v183 offset:54272
	ds_read_b128 v[238:241], v183 offset:55296
	ds_read_b128 v[242:245], v183 offset:56320
	global_load_lds_dwordx4 v[178:179], off
	s_add_i32 m0, s12, 0x2000
	s_add_u32 s10, s10, 0x40080
	v_lshl_add_u64 v[178:179], v[246:247], 0, s[24:25]
	s_addc_u32 s11, s11, 0
	s_add_i32 s12, s39, s46
	global_load_lds_dwordx4 v[178:179], off
	v_lshl_add_u64 v[178:179], s[10:11], 0, v[154:155]
	s_mov_b32 m0, s12
	s_nop 0
	global_load_lds_dwordx4 v[178:179], off
	v_lshl_add_u64 v[178:179], s[10:11], 0, v[158:159]
	s_add_i32 m0, s12, 0x2000
	s_nop 0
	global_load_lds_dwordx4 v[178:179], off
	v_lshl_add_u64 v[178:179], v[248:249], 0, s[24:25]
	s_mov_b32 m0, s51
	s_nop 0
	global_load_lds_dwordx4 v[178:179], off
	v_lshl_add_u64 v[178:179], v[250:251], 0, s[24:25]
	s_mov_b32 m0, s52
	s_nop 0
	global_load_lds_dwordx4 v[178:179], off
	s_waitcnt vmcnt(8)
	s_waitcnt lgkmcnt(0)
	s_barrier
	s_setprio 1
	s_waitcnt lgkmcnt(0)
	v_mfma_f32_16x16x32_bf16 v[60:63], v[128:131], v[214:217], v[60:63]
	v_mfma_f32_16x16x32_bf16 v[56:59], v[136:139], v[214:217], v[56:59]
	v_mfma_f32_16x16x32_bf16 v[44:47], v[128:131], v[222:225], v[44:47]
	v_mfma_f32_16x16x32_bf16 v[40:43], v[136:139], v[222:225], v[40:43]
	v_mfma_f32_16x16x32_bf16 v[28:31], v[128:131], v[230:233], v[28:31]
	v_mfma_f32_16x16x32_bf16 v[24:27], v[136:139], v[230:233], v[24:27]
	v_mfma_f32_16x16x32_bf16 v[12:15], v[128:131], v[238:241], v[12:15]
	v_mfma_f32_16x16x32_bf16 v[8:11], v[136:139], v[238:241], v[8:11]
	v_mfma_f32_16x16x32_bf16 v[60:63], v[132:135], v[218:221], v[60:63]
	v_mfma_f32_16x16x32_bf16 v[56:59], v[140:143], v[218:221], v[56:59]
	v_mfma_f32_16x16x32_bf16 v[44:47], v[132:135], v[226:229], v[44:47]
	v_mfma_f32_16x16x32_bf16 v[40:43], v[140:143], v[226:229], v[40:43]
	v_mfma_f32_16x16x32_bf16 v[28:31], v[132:135], v[234:237], v[28:31]
	v_mfma_f32_16x16x32_bf16 v[24:27], v[140:143], v[234:237], v[24:27]
	v_mfma_f32_16x16x32_bf16 v[12:15], v[132:135], v[242:245], v[12:15]
	v_mfma_f32_16x16x32_bf16 v[8:11], v[140:143], v[242:245], v[8:11]
	s_setprio 0
	s_setprio 1
	v_mfma_f32_16x16x32_bf16 v[52:55], v[170:173], v[214:217], v[52:55]
	v_mfma_f32_16x16x32_bf16 v[48:51], v[206:209], v[214:217], v[48:51]
	v_mfma_f32_16x16x32_bf16 v[36:39], v[170:173], v[222:225], v[36:39]
	v_mfma_f32_16x16x32_bf16 v[32:35], v[206:209], v[222:225], v[32:35]
	v_mfma_f32_16x16x32_bf16 v[20:23], v[170:173], v[230:233], v[20:23]
	v_mfma_f32_16x16x32_bf16 v[16:19], v[206:209], v[230:233], v[16:19]
	v_mfma_f32_16x16x32_bf16 v[4:7], v[170:173], v[238:241], v[4:7]
	v_mfma_f32_16x16x32_bf16 v[0:3], v[206:209], v[238:241], v[0:3]
	v_mfma_f32_16x16x32_bf16 v[52:55], v[174:177], v[218:221], v[52:55]
	v_mfma_f32_16x16x32_bf16 v[48:51], v[210:213], v[218:221], v[48:51]
	v_mfma_f32_16x16x32_bf16 v[36:39], v[174:177], v[226:229], v[36:39]
	v_mfma_f32_16x16x32_bf16 v[32:35], v[210:213], v[226:229], v[32:35]
	v_mfma_f32_16x16x32_bf16 v[20:23], v[174:177], v[234:237], v[20:23]
	v_mfma_f32_16x16x32_bf16 v[16:19], v[210:213], v[234:237], v[16:19]
	v_mfma_f32_16x16x32_bf16 v[4:7], v[174:177], v[242:245], v[4:7]
	v_mfma_f32_16x16x32_bf16 v[0:3], v[210:213], v[242:245], v[0:3]
	s_add_i32 s33, s33, 2
	s_add_u32 s8, s8, 0x100
	s_addc_u32 s9, s9, 0
	s_add_u32 s7, s7, 0x100
	s_addc_u32 s20, s20, 0
	s_cmp_gt_u32 s33, 13
	s_setprio 0
	s_barrier
	s_cbranch_scc0 .LBB0_102
	s_and_b64 vcc, exec, s[26:27]
	s_cbranch_vccz .LBB0_105
	s_barrier

.LBB0_643:
	ds_read_b128 v[150:153], v155
	ds_read_b128 v[164:167], v155 offset:1024
	ds_read_b128 v[168:171], v155 offset:2048
	ds_read_b128 v[172:175], v155 offset:3072
	ds_read_b128 v[176:179], v156
	ds_read_b128 v[182:185], v156 offset:1024
	ds_read_b128 v[186:189], v156 offset:2048
	ds_read_b128 v[190:193], v156 offset:3072
	s_add_u32 s34, s30, 0xfffc0080
	s_addc_u32 s35, s31, -1
	s_cmp_eq_u32 s52, 12
	s_cselect_b32 s37, s23, s35
	s_cselect_b32 s36, s29, s34
	s_cselect_b32 s35, s21, s51
	s_cselect_b32 s34, s49, s50
	v_lshl_add_u64 v[160:161], s[30:31], 0, v[136:137]
	s_add_i32 m0, s3, 0xc000
	ds_read_b128 v[194:197], v157
	ds_read_b128 v[198:201], v157 offset:1024
	ds_read_b128 v[202:205], v157 offset:2048
	ds_read_b128 v[206:209], v157 offset:3072
	ds_read_b128 v[210:213], v157 offset:4096
	ds_read_b128 v[214:217], v157 offset:5120
	ds_read_b128 v[218:221], v157 offset:6144
	ds_read_b128 v[222:225], v157 offset:7168
	global_load_lds_dwordx4 v[160:161], off
	v_lshl_add_u64 v[160:161], s[30:31], 0, v[138:139]
	s_add_i32 m0, s3, 0xe000
	s_nop 0
	global_load_lds_dwordx4 v[160:161], off
	s_waitcnt vmcnt(8)
	s_waitcnt lgkmcnt(0)
	s_barrier
	s_setprio 1
	s_waitcnt lgkmcnt(0)
	v_mfma_f32_16x16x32_bf16 v[124:127], v[150:153], v[194:197], v[124:127]
	v_mfma_f32_16x16x32_bf16 v[120:123], v[168:171], v[194:197], v[120:123]
	v_mfma_f32_16x16x32_bf16 v[108:111], v[150:153], v[202:205], v[108:111]
	v_mfma_f32_16x16x32_bf16 v[104:107], v[168:171], v[202:205], v[104:107]
	v_mfma_f32_16x16x32_bf16 v[92:95], v[150:153], v[210:213], v[92:95]
	v_mfma_f32_16x16x32_bf16 v[88:91], v[168:171], v[210:213], v[88:91]
	v_mfma_f32_16x16x32_bf16 v[76:79], v[150:153], v[218:221], v[76:79]
	v_mfma_f32_16x16x32_bf16 v[72:75], v[168:171], v[218:221], v[72:75]
	v_mfma_f32_16x16x32_bf16 v[124:127], v[164:167], v[198:201], v[124:127]
	v_mfma_f32_16x16x32_bf16 v[120:123], v[172:175], v[198:201], v[120:123]
	v_mfma_f32_16x16x32_bf16 v[108:111], v[164:167], v[206:209], v[108:111]
	v_mfma_f32_16x16x32_bf16 v[104:107], v[172:175], v[206:209], v[104:107]
	v_mfma_f32_16x16x32_bf16 v[92:95], v[164:167], v[214:217], v[92:95]
	v_mfma_f32_16x16x32_bf16 v[88:91], v[172:175], v[214:217], v[88:91]
	v_mfma_f32_16x16x32_bf16 v[76:79], v[164:167], v[222:225], v[76:79]
	v_mfma_f32_16x16x32_bf16 v[72:75], v[172:175], v[222:225], v[72:75]
	s_setprio 0
	s_setprio 1
	v_mfma_f32_16x16x32_bf16 v[116:119], v[176:179], v[194:197], v[116:119]
	v_mfma_f32_16x16x32_bf16 v[112:115], v[186:189], v[194:197], v[112:115]
	v_mfma_f32_16x16x32_bf16 v[100:103], v[176:179], v[202:205], v[100:103]
	v_mfma_f32_16x16x32_bf16 v[96:99], v[186:189], v[202:205], v[96:99]
	v_mfma_f32_16x16x32_bf16 v[84:87], v[176:179], v[210:213], v[84:87]
	v_mfma_f32_16x16x32_bf16 v[80:83], v[186:189], v[210:213], v[80:83]
	v_mfma_f32_16x16x32_bf16 v[68:71], v[176:179], v[218:221], v[68:71]
	v_mfma_f32_16x16x32_bf16 v[64:67], v[186:189], v[218:221], v[64:67]
	v_mfma_f32_16x16x32_bf16 v[116:119], v[182:185], v[198:201], v[116:119]
	v_mfma_f32_16x16x32_bf16 v[112:115], v[190:193], v[198:201], v[112:115]
	v_mfma_f32_16x16x32_bf16 v[100:103], v[182:185], v[206:209], v[100:103]
	v_mfma_f32_16x16x32_bf16 v[96:99], v[190:193], v[206:209], v[96:99]
	v_mfma_f32_16x16x32_bf16 v[84:87], v[182:185], v[214:217], v[84:87]
	v_mfma_f32_16x16x32_bf16 v[80:83], v[190:193], v[214:217], v[80:83]
	v_mfma_f32_16x16x32_bf16 v[68:71], v[182:185], v[222:225], v[68:71]
	v_mfma_f32_16x16x32_bf16 v[64:67], v[190:193], v[222:225], v[64:67]
	s_setprio 0
	s_barrier
	s_add_i32 s53, s46, s2
	v_lshl_add_u64 v[160:161], s[34:35], 0, v[130:131]
	s_mov_b32 m0, s53
	ds_read_b128 v[194:197], v157 offset:16384
	ds_read_b128 v[198:201], v157 offset:17408
	ds_read_b128 v[202:205], v157 offset:18432
	ds_read_b128 v[206:209], v157 offset:19456
	ds_read_b128 v[210:213], v157 offset:20480
	ds_read_b128 v[214:217], v157 offset:21504
	ds_read_b128 v[218:221], v157 offset:22528
	ds_read_b128 v[222:225], v157 offset:23552
	global_load_lds_dwordx4 v[160:161], off
	s_add_i32 m0, s53, 0x2000
	s_add_u32 s54, s34, 0x40000
	v_lshl_add_u64 v[226:227], s[34:35], 0, v[134:135]
	s_addc_u32 s55, s35, 0
	s_add_i32 s53, s47, s2
	global_load_lds_dwordx4 v[226:227], off
	v_lshl_add_u64 v[228:229], s[54:55], 0, v[130:131]
	s_mov_b32 m0, s53
	v_lshl_add_u64 v[230:231], s[36:37], 0, v[132:133]
	global_load_lds_dwordx4 v[228:229], off
	v_lshl_add_u64 v[228:229], s[54:55], 0, v[134:135]
	s_add_i32 m0, s53, 0x2000
	s_nop 0
	global_load_lds_dwordx4 v[228:229], off
	v_lshl_add_u64 v[228:229], s[36:37], 0, v[128:129]
	s_mov_b32 m0, s3
	s_nop 0
	global_load_lds_dwordx4 v[228:229], off
	s_mov_b32 m0, s33
	s_nop 0
	global_load_lds_dwordx4 v[230:231], off
	s_waitcnt vmcnt(8)
	s_waitcnt lgkmcnt(0)
	s_barrier
	s_setprio 1
	s_waitcnt lgkmcnt(0)
	v_mfma_f32_16x16x32_bf16 v[60:63], v[150:153], v[194:197], v[60:63]
	v_mfma_f32_16x16x32_bf16 v[56:59], v[168:171], v[194:197], v[56:59]
	v_mfma_f32_16x16x32_bf16 v[44:47], v[150:153], v[202:205], v[44:47]
	v_mfma_f32_16x16x32_bf16 v[40:43], v[168:171], v[202:205], v[40:43]
	v_mfma_f32_16x16x32_bf16 v[28:31], v[150:153], v[210:213], v[28:31]
	v_mfma_f32_16x16x32_bf16 v[24:27], v[168:171], v[210:213], v[24:27]
	v_mfma_f32_16x16x32_bf16 v[12:15], v[150:153], v[218:221], v[12:15]
	v_mfma_f32_16x16x32_bf16 v[8:11], v[168:171], v[218:221], v[8:11]
	v_mfma_f32_16x16x32_bf16 v[60:63], v[164:167], v[198:201], v[60:63]
	v_mfma_f32_16x16x32_bf16 v[56:59], v[172:175], v[198:201], v[56:59]
	v_mfma_f32_16x16x32_bf16 v[44:47], v[164:167], v[206:209], v[44:47]
	v_mfma_f32_16x16x32_bf16 v[40:43], v[172:175], v[206:209], v[40:43]
	v_mfma_f32_16x16x32_bf16 v[28:31], v[164:167], v[214:217], v[28:31]
	v_mfma_f32_16x16x32_bf16 v[24:27], v[172:175], v[214:217], v[24:27]
	v_mfma_f32_16x16x32_bf16 v[12:15], v[164:167], v[222:225], v[12:15]
	v_mfma_f32_16x16x32_bf16 v[8:11], v[172:175], v[222:225], v[8:11]
	s_setprio 0
	s_setprio 1
	v_mfma_f32_16x16x32_bf16 v[52:55], v[176:179], v[194:197], v[52:55]
	v_mfma_f32_16x16x32_bf16 v[48:51], v[186:189], v[194:197], v[48:51]
	v_mfma_f32_16x16x32_bf16 v[36:39], v[176:179], v[202:205], v[36:39]
	v_mfma_f32_16x16x32_bf16 v[32:35], v[186:189], v[202:205], v[32:35]
	v_mfma_f32_16x16x32_bf16 v[20:23], v[176:179], v[210:213], v[20:23]
	v_mfma_f32_16x16x32_bf16 v[16:19], v[186:189], v[210:213], v[16:19]
	v_mfma_f32_16x16x32_bf16 v[4:7], v[176:179], v[218:221], v[4:7]
	v_mfma_f32_16x16x32_bf16 v[0:3], v[186:189], v[218:221], v[0:3]
	v_mfma_f32_16x16x32_bf16 v[52:55], v[182:185], v[198:201], v[52:55]
	v_mfma_f32_16x16x32_bf16 v[48:51], v[190:193], v[198:201], v[48:51]
	v_mfma_f32_16x16x32_bf16 v[36:39], v[182:185], v[206:209], v[36:39]
	v_mfma_f32_16x16x32_bf16 v[32:35], v[190:193], v[206:209], v[32:35]
	v_mfma_f32_16x16x32_bf16 v[20:23], v[182:185], v[214:217], v[20:23]
	v_mfma_f32_16x16x32_bf16 v[16:19], v[190:193], v[214:217], v[16:19]
	v_mfma_f32_16x16x32_bf16 v[4:7], v[182:185], v[222:225], v[4:7]
	v_mfma_f32_16x16x32_bf16 v[0:3], v[190:193], v[222:225], v[0:3]
	s_setprio 0
	s_barrier
	s_add_i32 s53, 0, 0x18000
	v_add_u32_e32 v159, s53, v149
	s_add_i32 s54, 0, 0x1c000
	ds_read_b128 v[150:153], v159
	ds_read_b128 v[164:167], v159 offset:1024
	ds_read_b128 v[168:171], v159 offset:2048
	ds_read_b128 v[172:175], v159 offset:3072
	v_add_u32_e32 v159, s54, v149
	ds_read_b128 v[176:179], v159
	ds_read_b128 v[182:185], v159 offset:1024
	ds_read_b128 v[186:189], v159 offset:2048
	ds_read_b128 v[190:193], v159 offset:3072
	s_add_u32 s36, s36, 0x40000
	s_addc_u32 s37, s37, 0
	s_mov_b32 m0, s38
	v_lshl_add_u64 v[232:233], s[36:37], 0, v[128:129]
	ds_read_b128 v[194:197], v157 offset:32768
	ds_read_b128 v[198:201], v157 offset:33792
	ds_read_b128 v[202:205], v157 offset:34816
	ds_read_b128 v[206:209], v157 offset:35840
	ds_read_b128 v[210:213], v157 offset:36864
	ds_read_b128 v[214:217], v157 offset:37888
	ds_read_b128 v[218:221], v157 offset:38912
	ds_read_b128 v[222:225], v157 offset:39936
	global_load_lds_dwordx4 v[232:233], off
	v_lshl_add_u64 v[232:233], s[36:37], 0, v[132:133]
	s_mov_b32 m0, s39
	s_nop 0
	global_load_lds_dwordx4 v[232:233], off
	s_waitcnt vmcnt(8)
	s_waitcnt lgkmcnt(0)
	s_barrier
	s_setprio 1
	s_waitcnt lgkmcnt(0)
	v_mfma_f32_16x16x32_bf16 v[124:127], v[150:153], v[194:197], v[124:127]
	v_mfma_f32_16x16x32_bf16 v[120:123], v[168:171], v[194:197], v[120:123]
	v_mfma_f32_16x16x32_bf16 v[108:111], v[150:153], v[202:205], v[108:111]
	v_mfma_f32_16x16x32_bf16 v[104:107], v[168:171], v[202:205], v[104:107]
	v_mfma_f32_16x16x32_bf16 v[92:95], v[150:153], v[210:213], v[92:95]
	v_mfma_f32_16x16x32_bf16 v[88:91], v[168:171], v[210:213], v[88:91]
	v_mfma_f32_16x16x32_bf16 v[76:79], v[150:153], v[218:221], v[76:79]
	v_mfma_f32_16x16x32_bf16 v[72:75], v[168:171], v[218:221], v[72:75]
	v_mfma_f32_16x16x32_bf16 v[124:127], v[164:167], v[198:201], v[124:127]
	v_mfma_f32_16x16x32_bf16 v[120:123], v[172:175], v[198:201], v[120:123]
	v_mfma_f32_16x16x32_bf16 v[108:111], v[164:167], v[206:209], v[108:111]
	v_mfma_f32_16x16x32_bf16 v[104:107], v[172:175], v[206:209], v[104:107]
	v_mfma_f32_16x16x32_bf16 v[92:95], v[164:167], v[214:217], v[92:95]
	v_mfma_f32_16x16x32_bf16 v[88:91], v[172:175], v[214:217], v[88:91]
	v_mfma_f32_16x16x32_bf16 v[76:79], v[164:167], v[222:225], v[76:79]
	v_mfma_f32_16x16x32_bf16 v[72:75], v[172:175], v[222:225], v[72:75]
	s_setprio 0
	s_setprio 1
	v_mfma_f32_16x16x32_bf16 v[116:119], v[176:179], v[194:197], v[116:119]
	v_mfma_f32_16x16x32_bf16 v[112:115], v[186:189], v[194:197], v[112:115]
	v_mfma_f32_16x16x32_bf16 v[100:103], v[176:179], v[202:205], v[100:103]
	v_mfma_f32_16x16x32_bf16 v[96:99], v[186:189], v[202:205], v[96:99]
	v_mfma_f32_16x16x32_bf16 v[84:87], v[176:179], v[210:213], v[84:87]
	v_mfma_f32_16x16x32_bf16 v[80:83], v[186:189], v[210:213], v[80:83]
	v_mfma_f32_16x16x32_bf16 v[68:71], v[176:179], v[218:221], v[68:71]
	v_mfma_f32_16x16x32_bf16 v[64:67], v[186:189], v[218:221], v[64:67]
	v_mfma_f32_16x16x32_bf16 v[116:119], v[182:185], v[198:201], v[116:119]
	v_mfma_f32_16x16x32_bf16 v[112:115], v[190:193], v[198:201], v[112:115]
	v_mfma_f32_16x16x32_bf16 v[100:103], v[182:185], v[206:209], v[100:103]
	v_mfma_f32_16x16x32_bf16 v[96:99], v[190:193], v[206:209], v[96:99]
	v_mfma_f32_16x16x32_bf16 v[84:87], v[182:185], v[214:217], v[84:87]
	v_mfma_f32_16x16x32_bf16 v[80:83], v[190:193], v[214:217], v[80:83]
	v_mfma_f32_16x16x32_bf16 v[68:71], v[182:185], v[222:225], v[68:71]
	v_mfma_f32_16x16x32_bf16 v[64:67], v[190:193], v[222:225], v[64:67]
	s_setprio 0
	s_barrier
	s_add_i32 s36, s53, s2
	v_lshl_add_u64 v[160:161], v[160:161], 0, s[16:17]
	s_mov_b32 m0, s36
	ds_read_b128 v[194:197], v157 offset:49152
	ds_read_b128 v[198:201], v157 offset:50176
	ds_read_b128 v[202:205], v157 offset:51200
	ds_read_b128 v[206:209], v157 offset:52224
	ds_read_b128 v[210:213], v157 offset:53248
	ds_read_b128 v[214:217], v157 offset:54272
	ds_read_b128 v[218:221], v157 offset:55296
	ds_read_b128 v[222:225], v157 offset:56320
	global_load_lds_dwordx4 v[160:161], off
	s_add_i32 m0, s36, 0x2000
	s_add_u32 s34, s34, 0x40080
	v_lshl_add_u64 v[160:161], v[226:227], 0, s[16:17]
	s_addc_u32 s35, s35, 0
	s_add_i32 s36, s54, s2
	global_load_lds_dwordx4 v[160:161], off
	v_lshl_add_u64 v[160:161], s[34:35], 0, v[130:131]
	s_mov_b32 m0, s36
	s_nop 0
	global_load_lds_dwordx4 v[160:161], off
	v_lshl_add_u64 v[160:161], s[34:35], 0, v[134:135]
	s_add_i32 m0, s36, 0x2000
	s_nop 0
	global_load_lds_dwordx4 v[160:161], off
	v_lshl_add_u64 v[160:161], v[228:229], 0, s[16:17]
	s_mov_b32 m0, s41
	s_nop 0
	global_load_lds_dwordx4 v[160:161], off
	v_lshl_add_u64 v[160:161], v[230:231], 0, s[16:17]
	s_mov_b32 m0, s42
	s_nop 0
	global_load_lds_dwordx4 v[160:161], off
	s_waitcnt vmcnt(8)
	s_waitcnt lgkmcnt(0)
	s_barrier
	s_setprio 1
	s_waitcnt lgkmcnt(0)
	v_mfma_f32_16x16x32_bf16 v[60:63], v[150:153], v[194:197], v[60:63]
	v_mfma_f32_16x16x32_bf16 v[56:59], v[168:171], v[194:197], v[56:59]
	v_mfma_f32_16x16x32_bf16 v[44:47], v[150:153], v[202:205], v[44:47]
	v_mfma_f32_16x16x32_bf16 v[40:43], v[168:171], v[202:205], v[40:43]
	v_mfma_f32_16x16x32_bf16 v[28:31], v[150:153], v[210:213], v[28:31]
	v_mfma_f32_16x16x32_bf16 v[24:27], v[168:171], v[210:213], v[24:27]
	v_mfma_f32_16x16x32_bf16 v[12:15], v[150:153], v[218:221], v[12:15]
	v_mfma_f32_16x16x32_bf16 v[8:11], v[168:171], v[218:221], v[8:11]
	v_mfma_f32_16x16x32_bf16 v[60:63], v[164:167], v[198:201], v[60:63]
	v_mfma_f32_16x16x32_bf16 v[56:59], v[172:175], v[198:201], v[56:59]
	v_mfma_f32_16x16x32_bf16 v[44:47], v[164:167], v[206:209], v[44:47]
	v_mfma_f32_16x16x32_bf16 v[40:43], v[172:175], v[206:209], v[40:43]
	v_mfma_f32_16x16x32_bf16 v[28:31], v[164:167], v[214:217], v[28:31]
	v_mfma_f32_16x16x32_bf16 v[24:27], v[172:175], v[214:217], v[24:27]
	v_mfma_f32_16x16x32_bf16 v[12:15], v[164:167], v[222:225], v[12:15]
	v_mfma_f32_16x16x32_bf16 v[8:11], v[172:175], v[222:225], v[8:11]
	s_setprio 0
	s_setprio 1
	v_mfma_f32_16x16x32_bf16 v[52:55], v[176:179], v[194:197], v[52:55]
	v_mfma_f32_16x16x32_bf16 v[48:51], v[186:189], v[194:197], v[48:51]
	v_mfma_f32_16x16x32_bf16 v[36:39], v[176:179], v[202:205], v[36:39]
	v_mfma_f32_16x16x32_bf16 v[32:35], v[186:189], v[202:205], v[32:35]
	v_mfma_f32_16x16x32_bf16 v[20:23], v[176:179], v[210:213], v[20:23]
	v_mfma_f32_16x16x32_bf16 v[16:19], v[186:189], v[210:213], v[16:19]
	v_mfma_f32_16x16x32_bf16 v[4:7], v[176:179], v[218:221], v[4:7]
	v_mfma_f32_16x16x32_bf16 v[0:3], v[186:189], v[218:221], v[0:3]
	v_mfma_f32_16x16x32_bf16 v[52:55], v[182:185], v[198:201], v[52:55]
	v_mfma_f32_16x16x32_bf16 v[48:51], v[190:193], v[198:201], v[48:51]
	v_mfma_f32_16x16x32_bf16 v[36:39], v[182:185], v[206:209], v[36:39]
	v_mfma_f32_16x16x32_bf16 v[32:35], v[190:193], v[206:209], v[32:35]
	v_mfma_f32_16x16x32_bf16 v[20:23], v[182:185], v[214:217], v[20:23]
	v_mfma_f32_16x16x32_bf16 v[16:19], v[190:193], v[214:217], v[16:19]
	v_mfma_f32_16x16x32_bf16 v[4:7], v[182:185], v[222:225], v[4:7]
	v_mfma_f32_16x16x32_bf16 v[0:3], v[190:193], v[222:225], v[0:3]
	s_add_i32 s52, s52, 2
	s_add_u32 s30, s30, 0x100
	s_addc_u32 s31, s31, 0
	s_add_u32 s50, s50, 0x100
	s_addc_u32 s51, s51, 0
	s_cmp_gt_u32 s52, 13
	s_setprio 0
	s_barrier
	s_cbranch_scc0 .LBB0_643
	s_and_b64 vcc, exec, s[18:19]
	s_cbranch_vccz .LBB0_646
	s_barrier

.LBB0_857:
	ds_read_b128 v[154:157], v150
	ds_read_b128 v[158:161], v150 offset:1024
	ds_read_b128 v[164:167], v150 offset:2048
	ds_read_b128 v[168:171], v150 offset:3072
	ds_read_b128 v[172:175], v151
	ds_read_b128 v[176:179], v151 offset:1024
	ds_read_b128 v[180:183], v151 offset:2048
	ds_read_b128 v[184:187], v151 offset:3072
	s_add_u32 s28, s26, 0xfffc0080
	s_addc_u32 s29, s27, -1
	s_cmp_eq_u32 s50, 12
	s_cselect_b32 s31, s19, s29
	s_cselect_b32 s30, s46, s28
	s_cselect_b32 s29, s17, s49
	s_cselect_b32 s28, s47, s48
	v_lshl_add_u64 v[220:221], s[26:27], 0, v[138:139]
	s_add_i32 m0, s25, 0xc000
	ds_read_b128 v[188:191], v152
	ds_read_b128 v[192:195], v152 offset:1024
	ds_read_b128 v[196:199], v152 offset:2048
	ds_read_b128 v[200:203], v152 offset:3072
	ds_read_b128 v[204:207], v152 offset:4096
	ds_read_b128 v[208:211], v152 offset:5120
	ds_read_b128 v[212:215], v152 offset:6144
	ds_read_b128 v[216:219], v152 offset:7168
	global_load_lds_dwordx4 v[220:221], off
	v_lshl_add_u64 v[220:221], s[26:27], 0, v[140:141]
	s_add_i32 m0, s25, 0xe000
	s_nop 0
	global_load_lds_dwordx4 v[220:221], off
	s_waitcnt vmcnt(8)
	s_waitcnt lgkmcnt(0)
	s_barrier
	s_setprio 1
	s_waitcnt lgkmcnt(0)
	v_mfma_f32_16x16x32_bf16 v[124:127], v[154:157], v[188:191], v[124:127]
	v_mfma_f32_16x16x32_bf16 v[120:123], v[164:167], v[188:191], v[120:123]
	v_mfma_f32_16x16x32_bf16 v[108:111], v[154:157], v[196:199], v[108:111]
	v_mfma_f32_16x16x32_bf16 v[104:107], v[164:167], v[196:199], v[104:107]
	v_mfma_f32_16x16x32_bf16 v[92:95], v[154:157], v[204:207], v[92:95]
	v_mfma_f32_16x16x32_bf16 v[88:91], v[164:167], v[204:207], v[88:91]
	v_mfma_f32_16x16x32_bf16 v[76:79], v[154:157], v[212:215], v[76:79]
	v_mfma_f32_16x16x32_bf16 v[72:75], v[164:167], v[212:215], v[72:75]
	v_mfma_f32_16x16x32_bf16 v[124:127], v[158:161], v[192:195], v[124:127]
	v_mfma_f32_16x16x32_bf16 v[120:123], v[168:171], v[192:195], v[120:123]
	v_mfma_f32_16x16x32_bf16 v[108:111], v[158:161], v[200:203], v[108:111]
	v_mfma_f32_16x16x32_bf16 v[104:107], v[168:171], v[200:203], v[104:107]
	v_mfma_f32_16x16x32_bf16 v[92:95], v[158:161], v[208:211], v[92:95]
	v_mfma_f32_16x16x32_bf16 v[88:91], v[168:171], v[208:211], v[88:91]
	v_mfma_f32_16x16x32_bf16 v[76:79], v[158:161], v[216:219], v[76:79]
	v_mfma_f32_16x16x32_bf16 v[72:75], v[168:171], v[216:219], v[72:75]
	s_setprio 0
	s_setprio 1
	v_mfma_f32_16x16x32_bf16 v[116:119], v[172:175], v[188:191], v[116:119]
	v_mfma_f32_16x16x32_bf16 v[112:115], v[180:183], v[188:191], v[112:115]
	v_mfma_f32_16x16x32_bf16 v[100:103], v[172:175], v[196:199], v[100:103]
	v_mfma_f32_16x16x32_bf16 v[96:99], v[180:183], v[196:199], v[96:99]
	v_mfma_f32_16x16x32_bf16 v[84:87], v[172:175], v[204:207], v[84:87]
	v_mfma_f32_16x16x32_bf16 v[80:83], v[180:183], v[204:207], v[80:83]
	v_mfma_f32_16x16x32_bf16 v[68:71], v[172:175], v[212:215], v[68:71]
	v_mfma_f32_16x16x32_bf16 v[64:67], v[180:183], v[212:215], v[64:67]
	v_mfma_f32_16x16x32_bf16 v[116:119], v[176:179], v[192:195], v[116:119]
	v_mfma_f32_16x16x32_bf16 v[112:115], v[184:187], v[192:195], v[112:115]
	v_mfma_f32_16x16x32_bf16 v[100:103], v[176:179], v[200:203], v[100:103]
	v_mfma_f32_16x16x32_bf16 v[96:99], v[184:187], v[200:203], v[96:99]
	v_mfma_f32_16x16x32_bf16 v[84:87], v[176:179], v[208:211], v[84:87]
	v_mfma_f32_16x16x32_bf16 v[80:83], v[184:187], v[208:211], v[80:83]
	v_mfma_f32_16x16x32_bf16 v[68:71], v[176:179], v[216:219], v[68:71]
	v_mfma_f32_16x16x32_bf16 v[64:67], v[184:187], v[216:219], v[64:67]
	s_setprio 0
	s_barrier
	s_add_i32 s51, s42, s2
	v_lshl_add_u64 v[220:221], s[28:29], 0, v[134:135]
	s_mov_b32 m0, s51
	ds_read_b128 v[188:191], v152 offset:16384
	ds_read_b128 v[192:195], v152 offset:17408
	ds_read_b128 v[196:199], v152 offset:18432
	ds_read_b128 v[200:203], v152 offset:19456
	ds_read_b128 v[204:207], v152 offset:20480
	ds_read_b128 v[208:211], v152 offset:21504
	ds_read_b128 v[212:215], v152 offset:22528
	ds_read_b128 v[216:219], v152 offset:23552
	global_load_lds_dwordx4 v[220:221], off
	s_add_i32 m0, s51, 0x2000
	s_add_u32 s52, s28, 0x40000
	v_lshl_add_u64 v[222:223], s[28:29], 0, v[130:131]
	s_addc_u32 s53, s29, 0
	s_add_i32 s51, s43, s2
	global_load_lds_dwordx4 v[222:223], off
	v_lshl_add_u64 v[224:225], s[52:53], 0, v[134:135]
	s_mov_b32 m0, s51
	v_lshl_add_u64 v[226:227], s[30:31], 0, v[132:133]
	global_load_lds_dwordx4 v[224:225], off
	v_lshl_add_u64 v[224:225], s[52:53], 0, v[130:131]
	s_add_i32 m0, s51, 0x2000
	s_nop 0
	global_load_lds_dwordx4 v[224:225], off
	v_lshl_add_u64 v[224:225], s[30:31], 0, v[136:137]
	s_mov_b32 m0, s25
	s_nop 0
	global_load_lds_dwordx4 v[224:225], off
	s_mov_b32 m0, s34
	s_nop 0
	global_load_lds_dwordx4 v[226:227], off
	s_waitcnt vmcnt(8)
	s_waitcnt lgkmcnt(0)
	s_barrier
	s_setprio 1
	s_waitcnt lgkmcnt(0)
	v_mfma_f32_16x16x32_bf16 v[60:63], v[154:157], v[188:191], v[60:63]
	v_mfma_f32_16x16x32_bf16 v[56:59], v[164:167], v[188:191], v[56:59]
	v_mfma_f32_16x16x32_bf16 v[44:47], v[154:157], v[196:199], v[44:47]
	v_mfma_f32_16x16x32_bf16 v[40:43], v[164:167], v[196:199], v[40:43]
	v_mfma_f32_16x16x32_bf16 v[28:31], v[154:157], v[204:207], v[28:31]
	v_mfma_f32_16x16x32_bf16 v[24:27], v[164:167], v[204:207], v[24:27]
	v_mfma_f32_16x16x32_bf16 v[12:15], v[154:157], v[212:215], v[12:15]
	v_mfma_f32_16x16x32_bf16 v[8:11], v[164:167], v[212:215], v[8:11]
	v_mfma_f32_16x16x32_bf16 v[60:63], v[158:161], v[192:195], v[60:63]
	v_mfma_f32_16x16x32_bf16 v[56:59], v[168:171], v[192:195], v[56:59]
	v_mfma_f32_16x16x32_bf16 v[44:47], v[158:161], v[200:203], v[44:47]
	v_mfma_f32_16x16x32_bf16 v[40:43], v[168:171], v[200:203], v[40:43]
	v_mfma_f32_16x16x32_bf16 v[28:31], v[158:161], v[208:211], v[28:31]
	v_mfma_f32_16x16x32_bf16 v[24:27], v[168:171], v[208:211], v[24:27]
	v_mfma_f32_16x16x32_bf16 v[12:15], v[158:161], v[216:219], v[12:15]
	v_mfma_f32_16x16x32_bf16 v[8:11], v[168:171], v[216:219], v[8:11]
	s_setprio 0
	s_setprio 1
	v_mfma_f32_16x16x32_bf16 v[52:55], v[172:175], v[188:191], v[52:55]
	v_mfma_f32_16x16x32_bf16 v[48:51], v[180:183], v[188:191], v[48:51]
	v_mfma_f32_16x16x32_bf16 v[36:39], v[172:175], v[196:199], v[36:39]
	v_mfma_f32_16x16x32_bf16 v[32:35], v[180:183], v[196:199], v[32:35]
	v_mfma_f32_16x16x32_bf16 v[20:23], v[172:175], v[204:207], v[20:23]
	v_mfma_f32_16x16x32_bf16 v[16:19], v[180:183], v[204:207], v[16:19]
	v_mfma_f32_16x16x32_bf16 v[4:7], v[172:175], v[212:215], v[4:7]
	v_mfma_f32_16x16x32_bf16 v[0:3], v[180:183], v[212:215], v[0:3]
	v_mfma_f32_16x16x32_bf16 v[52:55], v[176:179], v[192:195], v[52:55]
	v_mfma_f32_16x16x32_bf16 v[48:51], v[184:187], v[192:195], v[48:51]
	v_mfma_f32_16x16x32_bf16 v[36:39], v[176:179], v[200:203], v[36:39]
	v_mfma_f32_16x16x32_bf16 v[32:35], v[184:187], v[200:203], v[32:35]
	v_mfma_f32_16x16x32_bf16 v[20:23], v[176:179], v[208:211], v[20:23]
	v_mfma_f32_16x16x32_bf16 v[16:19], v[184:187], v[208:211], v[16:19]
	v_mfma_f32_16x16x32_bf16 v[4:7], v[176:179], v[216:219], v[4:7]
	v_mfma_f32_16x16x32_bf16 v[0:3], v[184:187], v[216:219], v[0:3]
	s_setprio 0
	s_barrier
	s_add_i32 s51, 0, 0x18000
	v_add_u32_e32 v153, s51, v148
	s_add_i32 s52, 0, 0x1c000
	ds_read_b128 v[154:157], v153
	ds_read_b128 v[158:161], v153 offset:1024
	ds_read_b128 v[164:167], v153 offset:2048
	ds_read_b128 v[168:171], v153 offset:3072
	v_add_u32_e32 v153, s52, v148
	ds_read_b128 v[172:175], v153
	ds_read_b128 v[176:179], v153 offset:1024
	ds_read_b128 v[180:183], v153 offset:2048
	ds_read_b128 v[184:187], v153 offset:3072
	s_add_u32 s30, s30, 0x40000
	s_addc_u32 s31, s31, 0
	s_mov_b32 m0, s35
	v_lshl_add_u64 v[228:229], s[30:31], 0, v[136:137]
	ds_read_b128 v[188:191], v152 offset:32768
	ds_read_b128 v[192:195], v152 offset:33792
	ds_read_b128 v[196:199], v152 offset:34816
	ds_read_b128 v[200:203], v152 offset:35840
	ds_read_b128 v[204:207], v152 offset:36864
	ds_read_b128 v[208:211], v152 offset:37888
	ds_read_b128 v[212:215], v152 offset:38912
	ds_read_b128 v[216:219], v152 offset:39936
	global_load_lds_dwordx4 v[228:229], off
	v_lshl_add_u64 v[228:229], s[30:31], 0, v[132:133]
	s_mov_b32 m0, s36
	s_nop 0
	global_load_lds_dwordx4 v[228:229], off
	s_waitcnt vmcnt(8)
	s_waitcnt lgkmcnt(0)
	s_barrier
	s_setprio 1
	s_waitcnt lgkmcnt(0)
	v_mfma_f32_16x16x32_bf16 v[124:127], v[154:157], v[188:191], v[124:127]
	v_mfma_f32_16x16x32_bf16 v[120:123], v[164:167], v[188:191], v[120:123]
	v_mfma_f32_16x16x32_bf16 v[108:111], v[154:157], v[196:199], v[108:111]
	v_mfma_f32_16x16x32_bf16 v[104:107], v[164:167], v[196:199], v[104:107]
	v_mfma_f32_16x16x32_bf16 v[92:95], v[154:157], v[204:207], v[92:95]
	v_mfma_f32_16x16x32_bf16 v[88:91], v[164:167], v[204:207], v[88:91]
	v_mfma_f32_16x16x32_bf16 v[76:79], v[154:157], v[212:215], v[76:79]
	v_mfma_f32_16x16x32_bf16 v[72:75], v[164:167], v[212:215], v[72:75]
	v_mfma_f32_16x16x32_bf16 v[124:127], v[158:161], v[192:195], v[124:127]
	v_mfma_f32_16x16x32_bf16 v[120:123], v[168:171], v[192:195], v[120:123]
	v_mfma_f32_16x16x32_bf16 v[108:111], v[158:161], v[200:203], v[108:111]
	v_mfma_f32_16x16x32_bf16 v[104:107], v[168:171], v[200:203], v[104:107]
	v_mfma_f32_16x16x32_bf16 v[92:95], v[158:161], v[208:211], v[92:95]
	v_mfma_f32_16x16x32_bf16 v[88:91], v[168:171], v[208:211], v[88:91]
	v_mfma_f32_16x16x32_bf16 v[76:79], v[158:161], v[216:219], v[76:79]
	v_mfma_f32_16x16x32_bf16 v[72:75], v[168:171], v[216:219], v[72:75]
	s_setprio 0
	s_setprio 1
	v_mfma_f32_16x16x32_bf16 v[116:119], v[172:175], v[188:191], v[116:119]
	v_mfma_f32_16x16x32_bf16 v[112:115], v[180:183], v[188:191], v[112:115]
	v_mfma_f32_16x16x32_bf16 v[100:103], v[172:175], v[196:199], v[100:103]
	v_mfma_f32_16x16x32_bf16 v[96:99], v[180:183], v[196:199], v[96:99]
	v_mfma_f32_16x16x32_bf16 v[84:87], v[172:175], v[204:207], v[84:87]
	v_mfma_f32_16x16x32_bf16 v[80:83], v[180:183], v[204:207], v[80:83]
	v_mfma_f32_16x16x32_bf16 v[68:71], v[172:175], v[212:215], v[68:71]
	v_mfma_f32_16x16x32_bf16 v[64:67], v[180:183], v[212:215], v[64:67]
	v_mfma_f32_16x16x32_bf16 v[116:119], v[176:179], v[192:195], v[116:119]
	v_mfma_f32_16x16x32_bf16 v[112:115], v[184:187], v[192:195], v[112:115]
	v_mfma_f32_16x16x32_bf16 v[100:103], v[176:179], v[200:203], v[100:103]
	v_mfma_f32_16x16x32_bf16 v[96:99], v[184:187], v[200:203], v[96:99]
	v_mfma_f32_16x16x32_bf16 v[84:87], v[176:179], v[208:211], v[84:87]
	v_mfma_f32_16x16x32_bf16 v[80:83], v[184:187], v[208:211], v[80:83]
	v_mfma_f32_16x16x32_bf16 v[68:71], v[176:179], v[216:219], v[68:71]
	v_mfma_f32_16x16x32_bf16 v[64:67], v[184:187], v[216:219], v[64:67]
	s_setprio 0
	s_barrier
	s_add_i32 s30, s51, s2
	v_lshl_add_u64 v[220:221], v[220:221], 0, s[12:13]
	s_mov_b32 m0, s30
	ds_read_b128 v[188:191], v152 offset:49152
	ds_read_b128 v[192:195], v152 offset:50176
	ds_read_b128 v[196:199], v152 offset:51200
	ds_read_b128 v[200:203], v152 offset:52224
	ds_read_b128 v[204:207], v152 offset:53248
	ds_read_b128 v[208:211], v152 offset:54272
	ds_read_b128 v[212:215], v152 offset:55296
	ds_read_b128 v[216:219], v152 offset:56320
	global_load_lds_dwordx4 v[220:221], off
	s_add_i32 m0, s30, 0x2000
	s_add_u32 s28, s28, 0x40080
	v_lshl_add_u64 v[220:221], v[222:223], 0, s[12:13]
	s_addc_u32 s29, s29, 0
	s_add_i32 s30, s52, s2
	global_load_lds_dwordx4 v[220:221], off
	v_lshl_add_u64 v[220:221], s[28:29], 0, v[134:135]
	s_mov_b32 m0, s30
	s_nop 0
	global_load_lds_dwordx4 v[220:221], off
	v_lshl_add_u64 v[220:221], s[28:29], 0, v[130:131]
	s_add_i32 m0, s30, 0x2000
	s_nop 0
	global_load_lds_dwordx4 v[220:221], off
	v_lshl_add_u64 v[220:221], v[224:225], 0, s[12:13]
	s_mov_b32 m0, s38
	s_nop 0
	global_load_lds_dwordx4 v[220:221], off
	v_lshl_add_u64 v[220:221], v[226:227], 0, s[12:13]
	s_mov_b32 m0, s39
	s_nop 0
	global_load_lds_dwordx4 v[220:221], off
	s_waitcnt vmcnt(8)
	s_waitcnt lgkmcnt(0)
	s_barrier
	s_setprio 1
	s_waitcnt lgkmcnt(0)
	v_mfma_f32_16x16x32_bf16 v[60:63], v[154:157], v[188:191], v[60:63]
	v_mfma_f32_16x16x32_bf16 v[56:59], v[164:167], v[188:191], v[56:59]
	v_mfma_f32_16x16x32_bf16 v[44:47], v[154:157], v[196:199], v[44:47]
	v_mfma_f32_16x16x32_bf16 v[40:43], v[164:167], v[196:199], v[40:43]
	v_mfma_f32_16x16x32_bf16 v[28:31], v[154:157], v[204:207], v[28:31]
	v_mfma_f32_16x16x32_bf16 v[24:27], v[164:167], v[204:207], v[24:27]
	v_mfma_f32_16x16x32_bf16 v[12:15], v[154:157], v[212:215], v[12:15]
	v_mfma_f32_16x16x32_bf16 v[8:11], v[164:167], v[212:215], v[8:11]
	v_mfma_f32_16x16x32_bf16 v[60:63], v[158:161], v[192:195], v[60:63]
	v_mfma_f32_16x16x32_bf16 v[56:59], v[168:171], v[192:195], v[56:59]
	v_mfma_f32_16x16x32_bf16 v[44:47], v[158:161], v[200:203], v[44:47]
	v_mfma_f32_16x16x32_bf16 v[40:43], v[168:171], v[200:203], v[40:43]
	v_mfma_f32_16x16x32_bf16 v[28:31], v[158:161], v[208:211], v[28:31]
	v_mfma_f32_16x16x32_bf16 v[24:27], v[168:171], v[208:211], v[24:27]
	v_mfma_f32_16x16x32_bf16 v[12:15], v[158:161], v[216:219], v[12:15]
	v_mfma_f32_16x16x32_bf16 v[8:11], v[168:171], v[216:219], v[8:11]
	s_setprio 0
	s_setprio 1
	v_mfma_f32_16x16x32_bf16 v[52:55], v[172:175], v[188:191], v[52:55]
	v_mfma_f32_16x16x32_bf16 v[48:51], v[180:183], v[188:191], v[48:51]
	v_mfma_f32_16x16x32_bf16 v[36:39], v[172:175], v[196:199], v[36:39]
	v_mfma_f32_16x16x32_bf16 v[32:35], v[180:183], v[196:199], v[32:35]
	v_mfma_f32_16x16x32_bf16 v[20:23], v[172:175], v[204:207], v[20:23]
	v_mfma_f32_16x16x32_bf16 v[16:19], v[180:183], v[204:207], v[16:19]
	v_mfma_f32_16x16x32_bf16 v[4:7], v[172:175], v[212:215], v[4:7]
	v_mfma_f32_16x16x32_bf16 v[0:3], v[180:183], v[212:215], v[0:3]
	v_mfma_f32_16x16x32_bf16 v[52:55], v[176:179], v[192:195], v[52:55]
	v_mfma_f32_16x16x32_bf16 v[48:51], v[184:187], v[192:195], v[48:51]
	v_mfma_f32_16x16x32_bf16 v[36:39], v[176:179], v[200:203], v[36:39]
	v_mfma_f32_16x16x32_bf16 v[32:35], v[184:187], v[200:203], v[32:35]
	v_mfma_f32_16x16x32_bf16 v[20:23], v[176:179], v[208:211], v[20:23]
	v_mfma_f32_16x16x32_bf16 v[16:19], v[184:187], v[208:211], v[16:19]
	v_mfma_f32_16x16x32_bf16 v[4:7], v[176:179], v[216:219], v[4:7]
	v_mfma_f32_16x16x32_bf16 v[0:3], v[184:187], v[216:219], v[0:3]
	s_add_i32 s50, s50, 2
	s_add_u32 s26, s26, 0x100
	s_addc_u32 s27, s27, 0
	s_add_u32 s48, s48, 0x100
	s_addc_u32 s49, s49, 0
	s_cmp_gt_u32 s50, 13
	s_setprio 0
	s_barrier
	s_cbranch_scc0 .LBB0_857
	s_and_b64 vcc, exec, s[14:15]
	s_cbranch_vccz .LBB0_860
	s_barrier

.LBB0_939:
	ds_read_b128 v[148:151], v153
	ds_read_b128 v[158:161], v153 offset:1024
	ds_read_b128 v[162:165], v153 offset:2048
	ds_read_b128 v[166:169], v153 offset:3072
	ds_read_b128 v[170:173], v154
	ds_read_b128 v[174:177], v154 offset:1024
	ds_read_b128 v[178:181], v154 offset:2048
	ds_read_b128 v[182:185], v154 offset:3072
	s_add_u32 s26, s24, 0x100
	s_addc_u32 s27, s25, 0
	s_cmp_eq_u32 s50, 40
	s_cselect_b32 s31, s7, s27
	s_cselect_b32 s30, s6, s26
	s_cselect_b32 s29, s23, s49
	s_cselect_b32 s28, s22, s48
	v_lshl_add_u64 v[218:219], s[24:25], 0, v[138:139]
	s_add_i32 m0, s3, 0xc000
	ds_read_b128 v[186:189], v155
	ds_read_b128 v[190:193], v155 offset:1024
	ds_read_b128 v[194:197], v155 offset:2048
	ds_read_b128 v[198:201], v155 offset:3072
	ds_read_b128 v[202:205], v155 offset:4096
	ds_read_b128 v[206:209], v155 offset:5120
	ds_read_b128 v[210:213], v155 offset:6144
	ds_read_b128 v[214:217], v155 offset:7168
	global_load_lds_dwordx4 v[218:219], off
	v_lshl_add_u64 v[218:219], s[24:25], 0, v[140:141]
	s_add_i32 m0, s3, 0xe000
	s_nop 0
	global_load_lds_dwordx4 v[218:219], off
	s_waitcnt vmcnt(8)
	s_waitcnt lgkmcnt(0)
	s_barrier
	s_setprio 1
	s_waitcnt lgkmcnt(0)
	v_mfma_f32_16x16x32_bf16 v[124:127], v[148:151], v[186:189], v[124:127]
	v_mfma_f32_16x16x32_bf16 v[120:123], v[162:165], v[186:189], v[120:123]
	v_mfma_f32_16x16x32_bf16 v[108:111], v[148:151], v[194:197], v[108:111]
	v_mfma_f32_16x16x32_bf16 v[104:107], v[162:165], v[194:197], v[104:107]
	v_mfma_f32_16x16x32_bf16 v[92:95], v[148:151], v[202:205], v[92:95]
	v_mfma_f32_16x16x32_bf16 v[88:91], v[162:165], v[202:205], v[88:91]
	v_mfma_f32_16x16x32_bf16 v[76:79], v[148:151], v[210:213], v[76:79]
	v_mfma_f32_16x16x32_bf16 v[72:75], v[162:165], v[210:213], v[72:75]
	v_mfma_f32_16x16x32_bf16 v[124:127], v[158:161], v[190:193], v[124:127]
	v_mfma_f32_16x16x32_bf16 v[120:123], v[166:169], v[190:193], v[120:123]
	v_mfma_f32_16x16x32_bf16 v[108:111], v[158:161], v[198:201], v[108:111]
	v_mfma_f32_16x16x32_bf16 v[104:107], v[166:169], v[198:201], v[104:107]
	v_mfma_f32_16x16x32_bf16 v[92:95], v[158:161], v[206:209], v[92:95]
	v_mfma_f32_16x16x32_bf16 v[88:91], v[166:169], v[206:209], v[88:91]
	v_mfma_f32_16x16x32_bf16 v[76:79], v[158:161], v[214:217], v[76:79]
	v_mfma_f32_16x16x32_bf16 v[72:75], v[166:169], v[214:217], v[72:75]
	s_setprio 0
	s_setprio 1
	v_mfma_f32_16x16x32_bf16 v[116:119], v[170:173], v[186:189], v[116:119]
	v_mfma_f32_16x16x32_bf16 v[112:115], v[178:181], v[186:189], v[112:115]
	v_mfma_f32_16x16x32_bf16 v[100:103], v[170:173], v[194:197], v[100:103]
	v_mfma_f32_16x16x32_bf16 v[96:99], v[178:181], v[194:197], v[96:99]
	v_mfma_f32_16x16x32_bf16 v[84:87], v[170:173], v[202:205], v[84:87]
	v_mfma_f32_16x16x32_bf16 v[80:83], v[178:181], v[202:205], v[80:83]
	v_mfma_f32_16x16x32_bf16 v[68:71], v[170:173], v[210:213], v[68:71]
	v_mfma_f32_16x16x32_bf16 v[64:67], v[178:181], v[210:213], v[64:67]
	v_mfma_f32_16x16x32_bf16 v[116:119], v[174:177], v[190:193], v[116:119]
	v_mfma_f32_16x16x32_bf16 v[112:115], v[182:185], v[190:193], v[112:115]
	v_mfma_f32_16x16x32_bf16 v[100:103], v[174:177], v[198:201], v[100:103]
	v_mfma_f32_16x16x32_bf16 v[96:99], v[182:185], v[198:201], v[96:99]
	v_mfma_f32_16x16x32_bf16 v[84:87], v[174:177], v[206:209], v[84:87]
	v_mfma_f32_16x16x32_bf16 v[80:83], v[182:185], v[206:209], v[80:83]
	v_mfma_f32_16x16x32_bf16 v[68:71], v[174:177], v[214:217], v[68:71]
	v_mfma_f32_16x16x32_bf16 v[64:67], v[182:185], v[214:217], v[64:67]
	s_setprio 0
	s_barrier
	s_add_i32 s24, s42, s2
	v_lshl_add_u64 v[218:219], s[28:29], 0, v[132:133]
	s_mov_b32 m0, s24
	ds_read_b128 v[186:189], v155 offset:16384
	ds_read_b128 v[190:193], v155 offset:17408
	ds_read_b128 v[194:197], v155 offset:18432
	ds_read_b128 v[198:201], v155 offset:19456
	ds_read_b128 v[202:205], v155 offset:20480
	ds_read_b128 v[206:209], v155 offset:21504
	ds_read_b128 v[210:213], v155 offset:22528
	ds_read_b128 v[214:217], v155 offset:23552
	global_load_lds_dwordx4 v[218:219], off
	s_add_i32 m0, s24, 0x2000
	s_add_u32 s24, s28, 0xb0000
	v_lshl_add_u64 v[220:221], s[28:29], 0, v[136:137]
	s_addc_u32 s25, s29, 0
	s_add_i32 s51, s43, s2
	global_load_lds_dwordx4 v[220:221], off
	v_lshl_add_u64 v[222:223], s[24:25], 0, v[132:133]
	s_mov_b32 m0, s51
	v_lshl_add_u64 v[224:225], s[30:31], 0, v[134:135]
	global_load_lds_dwordx4 v[222:223], off
	v_lshl_add_u64 v[222:223], s[24:25], 0, v[136:137]
	s_add_i32 m0, s51, 0x2000
	s_nop 0
	global_load_lds_dwordx4 v[222:223], off
	v_lshl_add_u64 v[222:223], s[30:31], 0, v[130:131]
	s_mov_b32 m0, s3
	s_nop 0
	global_load_lds_dwordx4 v[222:223], off
	s_mov_b32 m0, s33
	s_nop 0
	global_load_lds_dwordx4 v[224:225], off
	s_waitcnt vmcnt(8)
	s_waitcnt lgkmcnt(0)
	s_barrier
	s_setprio 1
	s_waitcnt lgkmcnt(0)
	v_mfma_f32_16x16x32_bf16 v[60:63], v[148:151], v[186:189], v[60:63]
	v_mfma_f32_16x16x32_bf16 v[56:59], v[162:165], v[186:189], v[56:59]
	v_mfma_f32_16x16x32_bf16 v[44:47], v[148:151], v[194:197], v[44:47]
	v_mfma_f32_16x16x32_bf16 v[40:43], v[162:165], v[194:197], v[40:43]
	v_mfma_f32_16x16x32_bf16 v[28:31], v[148:151], v[202:205], v[28:31]
	v_mfma_f32_16x16x32_bf16 v[24:27], v[162:165], v[202:205], v[24:27]
	v_mfma_f32_16x16x32_bf16 v[12:15], v[148:151], v[210:213], v[12:15]
	v_mfma_f32_16x16x32_bf16 v[8:11], v[162:165], v[210:213], v[8:11]
	v_mfma_f32_16x16x32_bf16 v[60:63], v[158:161], v[190:193], v[60:63]
	v_mfma_f32_16x16x32_bf16 v[56:59], v[166:169], v[190:193], v[56:59]
	v_mfma_f32_16x16x32_bf16 v[44:47], v[158:161], v[198:201], v[44:47]
	v_mfma_f32_16x16x32_bf16 v[40:43], v[166:169], v[198:201], v[40:43]
	v_mfma_f32_16x16x32_bf16 v[28:31], v[158:161], v[206:209], v[28:31]
	v_mfma_f32_16x16x32_bf16 v[24:27], v[166:169], v[206:209], v[24:27]
	v_mfma_f32_16x16x32_bf16 v[12:15], v[158:161], v[214:217], v[12:15]
	v_mfma_f32_16x16x32_bf16 v[8:11], v[166:169], v[214:217], v[8:11]
	s_setprio 0
	s_setprio 1
	v_mfma_f32_16x16x32_bf16 v[52:55], v[170:173], v[186:189], v[52:55]
	v_mfma_f32_16x16x32_bf16 v[48:51], v[178:181], v[186:189], v[48:51]
	v_mfma_f32_16x16x32_bf16 v[36:39], v[170:173], v[194:197], v[36:39]
	v_mfma_f32_16x16x32_bf16 v[32:35], v[178:181], v[194:197], v[32:35]
	v_mfma_f32_16x16x32_bf16 v[20:23], v[170:173], v[202:205], v[20:23]
	v_mfma_f32_16x16x32_bf16 v[16:19], v[178:181], v[202:205], v[16:19]
	v_mfma_f32_16x16x32_bf16 v[4:7], v[170:173], v[210:213], v[4:7]
	v_mfma_f32_16x16x32_bf16 v[0:3], v[178:181], v[210:213], v[0:3]
	v_mfma_f32_16x16x32_bf16 v[52:55], v[174:177], v[190:193], v[52:55]
	v_mfma_f32_16x16x32_bf16 v[48:51], v[182:185], v[190:193], v[48:51]
	v_mfma_f32_16x16x32_bf16 v[36:39], v[174:177], v[198:201], v[36:39]
	v_mfma_f32_16x16x32_bf16 v[32:35], v[182:185], v[198:201], v[32:35]
	v_mfma_f32_16x16x32_bf16 v[20:23], v[174:177], v[206:209], v[20:23]
	v_mfma_f32_16x16x32_bf16 v[16:19], v[182:185], v[206:209], v[16:19]
	v_mfma_f32_16x16x32_bf16 v[4:7], v[174:177], v[214:217], v[4:7]
	v_mfma_f32_16x16x32_bf16 v[0:3], v[182:185], v[214:217], v[0:3]
	s_setprio 0
	s_barrier
	s_add_i32 s51, 0, 0x18000
	v_add_u32_e32 v157, s51, v145
	s_add_i32 s52, 0, 0x1c000
	ds_read_b128 v[148:151], v157
	ds_read_b128 v[158:161], v157 offset:1024
	ds_read_b128 v[162:165], v157 offset:2048
	ds_read_b128 v[166:169], v157 offset:3072
	v_add_u32_e32 v157, s52, v145
	ds_read_b128 v[170:173], v157
	ds_read_b128 v[174:177], v157 offset:1024
	ds_read_b128 v[178:181], v157 offset:2048
	ds_read_b128 v[182:185], v157 offset:3072
	s_add_u32 s24, s30, 0xb0000
	s_addc_u32 s25, s31, 0
	s_mov_b32 m0, s34
	v_lshl_add_u64 v[226:227], s[24:25], 0, v[130:131]
	ds_read_b128 v[186:189], v155 offset:32768
	ds_read_b128 v[190:193], v155 offset:33792
	ds_read_b128 v[194:197], v155 offset:34816
	ds_read_b128 v[198:201], v155 offset:35840
	ds_read_b128 v[202:205], v155 offset:36864
	ds_read_b128 v[206:209], v155 offset:37888
	ds_read_b128 v[210:213], v155 offset:38912
	ds_read_b128 v[214:217], v155 offset:39936
	global_load_lds_dwordx4 v[226:227], off
	v_lshl_add_u64 v[226:227], s[24:25], 0, v[134:135]
	s_mov_b32 m0, s35
	s_nop 0
	global_load_lds_dwordx4 v[226:227], off
	s_waitcnt vmcnt(8)
	s_waitcnt lgkmcnt(0)
	s_barrier
	s_setprio 1
	s_waitcnt lgkmcnt(0)
	v_mfma_f32_16x16x32_bf16 v[124:127], v[148:151], v[186:189], v[124:127]
	v_mfma_f32_16x16x32_bf16 v[120:123], v[162:165], v[186:189], v[120:123]
	v_mfma_f32_16x16x32_bf16 v[108:111], v[148:151], v[194:197], v[108:111]
	v_mfma_f32_16x16x32_bf16 v[104:107], v[162:165], v[194:197], v[104:107]
	v_mfma_f32_16x16x32_bf16 v[92:95], v[148:151], v[202:205], v[92:95]
	v_mfma_f32_16x16x32_bf16 v[88:91], v[162:165], v[202:205], v[88:91]
	v_mfma_f32_16x16x32_bf16 v[76:79], v[148:151], v[210:213], v[76:79]
	v_mfma_f32_16x16x32_bf16 v[72:75], v[162:165], v[210:213], v[72:75]
	v_mfma_f32_16x16x32_bf16 v[124:127], v[158:161], v[190:193], v[124:127]
	v_mfma_f32_16x16x32_bf16 v[120:123], v[166:169], v[190:193], v[120:123]
	v_mfma_f32_16x16x32_bf16 v[108:111], v[158:161], v[198:201], v[108:111]
	v_mfma_f32_16x16x32_bf16 v[104:107], v[166:169], v[198:201], v[104:107]
	v_mfma_f32_16x16x32_bf16 v[92:95], v[158:161], v[206:209], v[92:95]
	v_mfma_f32_16x16x32_bf16 v[88:91], v[166:169], v[206:209], v[88:91]
	v_mfma_f32_16x16x32_bf16 v[76:79], v[158:161], v[214:217], v[76:79]
	v_mfma_f32_16x16x32_bf16 v[72:75], v[166:169], v[214:217], v[72:75]
	s_setprio 0
	s_setprio 1
	v_mfma_f32_16x16x32_bf16 v[116:119], v[170:173], v[186:189], v[116:119]
	v_mfma_f32_16x16x32_bf16 v[112:115], v[178:181], v[186:189], v[112:115]
	v_mfma_f32_16x16x32_bf16 v[100:103], v[170:173], v[194:197], v[100:103]
	v_mfma_f32_16x16x32_bf16 v[96:99], v[178:181], v[194:197], v[96:99]
	v_mfma_f32_16x16x32_bf16 v[84:87], v[170:173], v[202:205], v[84:87]
	v_mfma_f32_16x16x32_bf16 v[80:83], v[178:181], v[202:205], v[80:83]
	v_mfma_f32_16x16x32_bf16 v[68:71], v[170:173], v[210:213], v[68:71]
	v_mfma_f32_16x16x32_bf16 v[64:67], v[178:181], v[210:213], v[64:67]
	v_mfma_f32_16x16x32_bf16 v[116:119], v[174:177], v[190:193], v[116:119]
	v_mfma_f32_16x16x32_bf16 v[112:115], v[182:185], v[190:193], v[112:115]
	v_mfma_f32_16x16x32_bf16 v[100:103], v[174:177], v[198:201], v[100:103]
	v_mfma_f32_16x16x32_bf16 v[96:99], v[182:185], v[198:201], v[96:99]
	v_mfma_f32_16x16x32_bf16 v[84:87], v[174:177], v[206:209], v[84:87]
	v_mfma_f32_16x16x32_bf16 v[80:83], v[182:185], v[206:209], v[80:83]
	v_mfma_f32_16x16x32_bf16 v[68:71], v[174:177], v[214:217], v[68:71]
	v_mfma_f32_16x16x32_bf16 v[64:67], v[182:185], v[214:217], v[64:67]
	s_setprio 0
	s_barrier
	s_add_i32 s24, s51, s2
	v_lshl_add_u64 v[218:219], v[218:219], 0, s[18:19]
	s_mov_b32 m0, s24
	ds_read_b128 v[186:189], v155 offset:49152
	ds_read_b128 v[190:193], v155 offset:50176
	ds_read_b128 v[194:197], v155 offset:51200
	ds_read_b128 v[198:201], v155 offset:52224
	ds_read_b128 v[202:205], v155 offset:53248
	ds_read_b128 v[206:209], v155 offset:54272
	ds_read_b128 v[210:213], v155 offset:55296
	ds_read_b128 v[214:217], v155 offset:56320
	global_load_lds_dwordx4 v[218:219], off
	s_add_i32 m0, s24, 0x2000
	s_add_u32 s24, s28, 0xb0080
	v_lshl_add_u64 v[218:219], v[220:221], 0, s[18:19]
	s_addc_u32 s25, s29, 0
	s_add_i32 s28, s52, s2
	global_load_lds_dwordx4 v[218:219], off
	v_lshl_add_u64 v[218:219], s[24:25], 0, v[132:133]
	s_mov_b32 m0, s28
	s_nop 0
	global_load_lds_dwordx4 v[218:219], off
	v_lshl_add_u64 v[218:219], s[24:25], 0, v[136:137]
	s_add_i32 m0, s28, 0x2000
	s_nop 0
	global_load_lds_dwordx4 v[218:219], off
	v_lshl_add_u64 v[218:219], v[222:223], 0, s[18:19]
	s_mov_b32 m0, s37
	s_nop 0
	global_load_lds_dwordx4 v[218:219], off
	v_lshl_add_u64 v[218:219], v[224:225], 0, s[18:19]
	s_mov_b32 m0, s38
	s_nop 0
	global_load_lds_dwordx4 v[218:219], off
	s_waitcnt vmcnt(8)
	s_waitcnt lgkmcnt(0)
	s_barrier
	s_setprio 1
	s_waitcnt lgkmcnt(0)
	v_mfma_f32_16x16x32_bf16 v[60:63], v[148:151], v[186:189], v[60:63]
	v_mfma_f32_16x16x32_bf16 v[56:59], v[162:165], v[186:189], v[56:59]
	v_mfma_f32_16x16x32_bf16 v[44:47], v[148:151], v[194:197], v[44:47]
	v_mfma_f32_16x16x32_bf16 v[40:43], v[162:165], v[194:197], v[40:43]
	v_mfma_f32_16x16x32_bf16 v[28:31], v[148:151], v[202:205], v[28:31]
	v_mfma_f32_16x16x32_bf16 v[24:27], v[162:165], v[202:205], v[24:27]
	v_mfma_f32_16x16x32_bf16 v[12:15], v[148:151], v[210:213], v[12:15]
	v_mfma_f32_16x16x32_bf16 v[8:11], v[162:165], v[210:213], v[8:11]
	v_mfma_f32_16x16x32_bf16 v[60:63], v[158:161], v[190:193], v[60:63]
	v_mfma_f32_16x16x32_bf16 v[56:59], v[166:169], v[190:193], v[56:59]
	v_mfma_f32_16x16x32_bf16 v[44:47], v[158:161], v[198:201], v[44:47]
	v_mfma_f32_16x16x32_bf16 v[40:43], v[166:169], v[198:201], v[40:43]
	v_mfma_f32_16x16x32_bf16 v[28:31], v[158:161], v[206:209], v[28:31]
	v_mfma_f32_16x16x32_bf16 v[24:27], v[166:169], v[206:209], v[24:27]
	v_mfma_f32_16x16x32_bf16 v[12:15], v[158:161], v[214:217], v[12:15]
	v_mfma_f32_16x16x32_bf16 v[8:11], v[166:169], v[214:217], v[8:11]
	s_setprio 0
	s_setprio 1
	v_mfma_f32_16x16x32_bf16 v[52:55], v[170:173], v[186:189], v[52:55]
	v_mfma_f32_16x16x32_bf16 v[48:51], v[178:181], v[186:189], v[48:51]
	v_mfma_f32_16x16x32_bf16 v[36:39], v[170:173], v[194:197], v[36:39]
	v_mfma_f32_16x16x32_bf16 v[32:35], v[178:181], v[194:197], v[32:35]
	v_mfma_f32_16x16x32_bf16 v[20:23], v[170:173], v[202:205], v[20:23]
	v_mfma_f32_16x16x32_bf16 v[16:19], v[178:181], v[202:205], v[16:19]
	v_mfma_f32_16x16x32_bf16 v[4:7], v[170:173], v[210:213], v[4:7]
	v_mfma_f32_16x16x32_bf16 v[0:3], v[178:181], v[210:213], v[0:3]
	v_mfma_f32_16x16x32_bf16 v[52:55], v[174:177], v[190:193], v[52:55]
	v_mfma_f32_16x16x32_bf16 v[48:51], v[182:185], v[190:193], v[48:51]
	v_mfma_f32_16x16x32_bf16 v[36:39], v[174:177], v[198:201], v[36:39]
	v_mfma_f32_16x16x32_bf16 v[32:35], v[182:185], v[198:201], v[32:35]
	v_mfma_f32_16x16x32_bf16 v[20:23], v[174:177], v[206:209], v[20:23]
	v_mfma_f32_16x16x32_bf16 v[16:19], v[182:185], v[206:209], v[16:19]
	v_mfma_f32_16x16x32_bf16 v[4:7], v[174:177], v[214:217], v[4:7]
	v_mfma_f32_16x16x32_bf16 v[0:3], v[182:185], v[214:217], v[0:3]
	s_add_i32 s50, s50, 2
	s_add_u32 s48, s48, 0x100
	s_addc_u32 s49, s49, 0
	s_cmp_gt_u32 s50, 41
	s_mov_b64 s[24:25], s[26:27]
	s_setprio 0
	s_barrier
	s_cbranch_scc0 .LBB0_939
	s_and_b64 vcc, exec, s[20:21]
	s_cbranch_vccz .LBB0_942
	s_barrier
